# EpiRes epilogue row-sum partials reduced across row groups with permlane swaps instead of ds_bpermute
# speedup vs baseline: 1.0018x; 1.0018x over previous
.LBB0_622:
	s_lshl_b32 s66, s48, 2
	v_cndmask_b32_e64 v144, 0, 1, s[20:21]
	v_cmp_ne_u32_e64 s[12:13], 1, v144
	s_andn2_b64 vcc, exec, s[20:21]
	s_ashr_i32 s67, s66, 31
	s_cbranch_vccnz .LBB0_626
	v_mul_f32_e32 v124, v124, v124
	v_mul_f32_e32 v120, v120, v120
	v_mul_f32_e32 v112, v112, v112
	v_fmac_f32_e32 v124, v125, v125
	v_fmac_f32_e32 v120, v121, v121
	v_mul_f32_e32 v116, v116, v116
	v_fmac_f32_e32 v112, v113, v113
	v_fmac_f32_e32 v124, v126, v126
	v_fmac_f32_e32 v120, v122, v122
	v_fmac_f32_e32 v116, v117, v117
	v_fmac_f32_e32 v112, v114, v114
	v_and_b32_e32 v114, 64, v197
	v_fmac_f32_e32 v124, v127, v127
	v_fmac_f32_e32 v120, v123, v123
	v_fmac_f32_e32 v116, v118, v118
	v_xor_b32_e32 v113, 16, v197
	v_add_u32_e32 v114, 64, v114
	v_add_f32_e32 v120, v124, v120
	v_fmac_f32_e32 v116, v119, v119
	v_cmp_lt_i32_e32 vcc, v113, v114
	v_add_f32_e32 v116, v120, v116
	v_fmac_f32_e32 v112, v115, v115
	v_cndmask_b32_e32 v113, v197, v113, vcc
	v_add_f32_e32 v112, v116, v112
	v_lshlrev_b32_e32 v113, 2, v113
	v_mov_b32_e32 v113, v112
	s_nop 1
	v_permlane16_swap_b32_e32 v112, v113
	s_nop 0
	s_waitcnt lgkmcnt(0)
	v_add_f32_e32 v112, v112, v113
	v_xor_b32_e32 v113, 32, v197
	v_cmp_lt_i32_e32 vcc, v113, v114
	s_nop 1
	v_cndmask_b32_e32 v113, v197, v113, vcc
	v_lshlrev_b32_e32 v113, 2, v113
	v_mov_b32_e32 v113, v112
	s_nop 1
	v_permlane32_swap_b32_e32 v112, v113
	s_nop 0
	s_and_saveexec_b64 s[72:73], s[6:7]
	s_cbranch_execz .LBB0_625
	v_lshlrev_b64 v[114:115], 6, v[142:143]
	v_lshl_add_u64 v[114:115], s[94:95], 0, v[114:115]
	v_lshl_add_u64 v[114:115], s[66:67], 2, v[114:115]
	s_lshl_b32 s48, s87, 2
	v_lshl_add_u64 v[114:115], v[114:115], 0, s[48:49]
	s_waitcnt lgkmcnt(0)
	v_add_f32_e32 v112, v112, v113
	global_store_dword v[114:115], v112, off

.LBB0_643:
	v_mul_f32_e32 v108, v108, v108
	v_mul_f32_e32 v104, v104, v104
	v_mul_f32_e32 v96, v96, v96
	v_fmac_f32_e32 v108, v109, v109
	v_fmac_f32_e32 v104, v105, v105
	v_mul_f32_e32 v100, v100, v100
	v_fmac_f32_e32 v96, v97, v97
	v_fmac_f32_e32 v108, v110, v110
	v_fmac_f32_e32 v104, v106, v106
	v_fmac_f32_e32 v100, v101, v101
	v_fmac_f32_e32 v96, v98, v98
	v_and_b32_e32 v98, 64, v197
	v_fmac_f32_e32 v108, v111, v111
	v_fmac_f32_e32 v104, v107, v107
	v_fmac_f32_e32 v100, v102, v102
	v_xor_b32_e32 v97, 16, v197
	v_add_u32_e32 v98, 64, v98
	v_add_f32_e32 v104, v108, v104
	v_fmac_f32_e32 v100, v103, v103
	v_cmp_lt_i32_e32 vcc, v97, v98
	v_add_f32_e32 v100, v104, v100
	v_fmac_f32_e32 v96, v99, v99
	v_cndmask_b32_e32 v97, v197, v97, vcc
	v_add_f32_e32 v96, v100, v96
	v_lshlrev_b32_e32 v97, 2, v97
	v_mov_b32_e32 v97, v96
	s_nop 1
	v_permlane16_swap_b32_e32 v96, v97
	s_nop 0
	s_waitcnt lgkmcnt(0)
	v_add_f32_e32 v96, v96, v97
	v_xor_b32_e32 v97, 32, v197
	v_cmp_lt_i32_e32 vcc, v97, v98
	s_nop 1
	v_cndmask_b32_e32 v97, v197, v97, vcc
	v_lshlrev_b32_e32 v97, 2, v97
	v_mov_b32_e32 v97, v96
	s_nop 1
	v_permlane32_swap_b32_e32 v96, v97
	s_nop 0
	s_and_saveexec_b64 s[72:73], s[6:7]
	s_cbranch_execz .LBB0_645
	v_lshlrev_b64 v[98:99], 6, v[112:113]
	v_lshl_add_u64 v[98:99], s[94:95], 0, v[98:99]
	v_lshl_add_u64 v[98:99], s[66:67], 2, v[98:99]
	s_lshl_b32 s48, s87, 2
	v_lshl_add_u64 v[98:99], v[98:99], 0, s[48:49]
	s_waitcnt lgkmcnt(0)
	v_add_f32_e32 v96, v96, v97
	global_store_dword v[98:99], v96, off

.LBB0_663:
	v_mul_f32_e32 v92, v92, v92
	v_mul_f32_e32 v88, v88, v88
	v_mul_f32_e32 v80, v80, v80
	v_fmac_f32_e32 v92, v93, v93
	v_fmac_f32_e32 v88, v89, v89
	v_mul_f32_e32 v84, v84, v84
	v_fmac_f32_e32 v80, v81, v81
	v_fmac_f32_e32 v92, v94, v94
	v_fmac_f32_e32 v88, v90, v90
	v_fmac_f32_e32 v84, v85, v85
	v_fmac_f32_e32 v80, v82, v82
	v_and_b32_e32 v82, 64, v197
	v_fmac_f32_e32 v92, v95, v95
	v_fmac_f32_e32 v88, v91, v91
	v_fmac_f32_e32 v84, v86, v86
	v_xor_b32_e32 v81, 16, v197
	v_add_u32_e32 v82, 64, v82
	v_add_f32_e32 v88, v92, v88
	v_fmac_f32_e32 v84, v87, v87
	v_cmp_lt_i32_e32 vcc, v81, v82
	v_add_f32_e32 v84, v88, v84
	v_fmac_f32_e32 v80, v83, v83
	v_cndmask_b32_e32 v81, v197, v81, vcc
	v_add_f32_e32 v80, v84, v80
	v_lshlrev_b32_e32 v81, 2, v81
	v_mov_b32_e32 v81, v80
	s_nop 1
	v_permlane16_swap_b32_e32 v80, v81
	s_nop 0
	s_waitcnt lgkmcnt(0)
	v_add_f32_e32 v80, v80, v81
	v_xor_b32_e32 v81, 32, v197
	v_cmp_lt_i32_e32 vcc, v81, v82
	s_nop 1
	v_cndmask_b32_e32 v81, v197, v81, vcc
	v_lshlrev_b32_e32 v81, 2, v81
	v_mov_b32_e32 v81, v80
	s_nop 1
	v_permlane32_swap_b32_e32 v80, v81
	s_nop 0
	s_and_saveexec_b64 s[72:73], s[6:7]
	s_cbranch_execz .LBB0_665
	v_lshlrev_b64 v[82:83], 6, v[96:97]
	v_lshl_add_u64 v[82:83], s[94:95], 0, v[82:83]
	v_lshl_add_u64 v[82:83], s[66:67], 2, v[82:83]
	s_lshl_b32 s48, s87, 2
	v_lshl_add_u64 v[82:83], v[82:83], 0, s[48:49]
	s_waitcnt lgkmcnt(0)
	v_add_f32_e32 v80, v80, v81
	global_store_dword v[82:83], v80, off

.LBB0_683:
	v_mul_f32_e32 v76, v76, v76
	v_mul_f32_e32 v72, v72, v72
	v_mul_f32_e32 v64, v64, v64
	v_fmac_f32_e32 v76, v77, v77
	v_fmac_f32_e32 v72, v73, v73
	v_mul_f32_e32 v68, v68, v68
	v_fmac_f32_e32 v64, v65, v65
	v_fmac_f32_e32 v76, v78, v78
	v_fmac_f32_e32 v72, v74, v74
	v_fmac_f32_e32 v68, v69, v69
	v_fmac_f32_e32 v64, v66, v66
	v_and_b32_e32 v66, 64, v197
	v_fmac_f32_e32 v76, v79, v79
	v_fmac_f32_e32 v72, v75, v75
	v_fmac_f32_e32 v68, v70, v70
	v_xor_b32_e32 v65, 16, v197
	v_add_u32_e32 v66, 64, v66
	v_add_f32_e32 v72, v76, v72
	v_fmac_f32_e32 v68, v71, v71
	v_cmp_lt_i32_e32 vcc, v65, v66
	v_add_f32_e32 v68, v72, v68
	v_fmac_f32_e32 v64, v67, v67
	v_cndmask_b32_e32 v65, v197, v65, vcc
	v_add_f32_e32 v64, v68, v64
	v_lshlrev_b32_e32 v65, 2, v65
	v_mov_b32_e32 v65, v64
	s_nop 1
	v_permlane16_swap_b32_e32 v64, v65
	s_nop 0
	s_waitcnt lgkmcnt(0)
	v_add_f32_e32 v64, v64, v65
	v_xor_b32_e32 v65, 32, v197
	v_cmp_lt_i32_e32 vcc, v65, v66
	s_nop 1
	v_cndmask_b32_e32 v65, v197, v65, vcc
	v_lshlrev_b32_e32 v65, 2, v65
	v_mov_b32_e32 v65, v64
	s_nop 1
	v_permlane32_swap_b32_e32 v64, v65
	s_nop 0
	s_and_saveexec_b64 s[72:73], s[6:7]
	s_cbranch_execz .LBB0_685
	v_lshlrev_b64 v[66:67], 6, v[80:81]
	v_lshl_add_u64 v[66:67], s[94:95], 0, v[66:67]
	v_lshl_add_u64 v[66:67], s[66:67], 2, v[66:67]
	s_lshl_b32 s48, s87, 2
	v_lshl_add_u64 v[66:67], v[66:67], 0, s[48:49]
	s_waitcnt lgkmcnt(0)
	v_add_f32_e32 v64, v64, v65
	global_store_dword v[66:67], v64, off

.LBB0_703:
	v_mul_f32_e32 v60, v60, v60
	v_mul_f32_e32 v56, v56, v56
	v_mul_f32_e32 v48, v48, v48
	v_fmac_f32_e32 v60, v61, v61
	v_fmac_f32_e32 v56, v57, v57
	v_mul_f32_e32 v52, v52, v52
	v_fmac_f32_e32 v48, v49, v49
	v_fmac_f32_e32 v60, v62, v62
	v_fmac_f32_e32 v56, v58, v58
	v_fmac_f32_e32 v52, v53, v53
	v_fmac_f32_e32 v48, v50, v50
	v_and_b32_e32 v50, 64, v197
	v_fmac_f32_e32 v60, v63, v63
	v_fmac_f32_e32 v56, v59, v59
	v_fmac_f32_e32 v52, v54, v54
	v_xor_b32_e32 v49, 16, v197
	v_add_u32_e32 v50, 64, v50
	v_add_f32_e32 v56, v60, v56
	v_fmac_f32_e32 v52, v55, v55
	v_cmp_lt_i32_e32 vcc, v49, v50
	v_add_f32_e32 v52, v56, v52
	v_fmac_f32_e32 v48, v51, v51
	v_cndmask_b32_e32 v49, v197, v49, vcc
	v_add_f32_e32 v48, v52, v48
	v_lshlrev_b32_e32 v49, 2, v49
	v_mov_b32_e32 v49, v48
	s_nop 1
	v_permlane16_swap_b32_e32 v48, v49
	s_nop 0
	s_waitcnt lgkmcnt(0)
	v_add_f32_e32 v48, v48, v49
	v_xor_b32_e32 v49, 32, v197
	v_cmp_lt_i32_e32 vcc, v49, v50
	s_nop 1
	v_cndmask_b32_e32 v49, v197, v49, vcc
	v_lshlrev_b32_e32 v49, 2, v49
	v_mov_b32_e32 v49, v48
	s_nop 1
	v_permlane32_swap_b32_e32 v48, v49
	s_nop 0
	s_and_saveexec_b64 s[72:73], s[6:7]
	s_cbranch_execz .LBB0_705
	v_lshlrev_b64 v[50:51], 6, v[64:65]
	v_lshl_add_u64 v[50:51], s[94:95], 0, v[50:51]
	v_lshl_add_u64 v[50:51], s[66:67], 2, v[50:51]
	s_lshl_b32 s48, s87, 2
	v_lshl_add_u64 v[50:51], v[50:51], 0, s[48:49]
	s_waitcnt lgkmcnt(0)
	v_add_f32_e32 v48, v48, v49
	global_store_dword v[50:51], v48, off

.LBB0_723:
	v_mul_f32_e32 v44, v44, v44
	v_mul_f32_e32 v40, v40, v40
	v_mul_f32_e32 v32, v32, v32
	v_fmac_f32_e32 v44, v45, v45
	v_fmac_f32_e32 v40, v41, v41
	v_mul_f32_e32 v36, v36, v36
	v_fmac_f32_e32 v32, v33, v33
	v_fmac_f32_e32 v44, v46, v46
	v_fmac_f32_e32 v40, v42, v42
	v_fmac_f32_e32 v36, v37, v37
	v_fmac_f32_e32 v32, v34, v34
	v_and_b32_e32 v34, 64, v197
	v_fmac_f32_e32 v44, v47, v47
	v_fmac_f32_e32 v40, v43, v43
	v_fmac_f32_e32 v36, v38, v38
	v_xor_b32_e32 v33, 16, v197
	v_add_u32_e32 v34, 64, v34
	v_add_f32_e32 v40, v44, v40
	v_fmac_f32_e32 v36, v39, v39
	v_cmp_lt_i32_e32 vcc, v33, v34
	v_add_f32_e32 v36, v40, v36
	v_fmac_f32_e32 v32, v35, v35
	v_cndmask_b32_e32 v33, v197, v33, vcc
	v_add_f32_e32 v32, v36, v32
	v_lshlrev_b32_e32 v33, 2, v33
	v_mov_b32_e32 v33, v32
	s_nop 1
	v_permlane16_swap_b32_e32 v32, v33
	s_nop 0
	s_waitcnt lgkmcnt(0)
	v_add_f32_e32 v32, v32, v33
	v_xor_b32_e32 v33, 32, v197
	v_cmp_lt_i32_e32 vcc, v33, v34
	s_nop 1
	v_cndmask_b32_e32 v33, v197, v33, vcc
	v_lshlrev_b32_e32 v33, 2, v33
	v_mov_b32_e32 v33, v32
	s_nop 1
	v_permlane32_swap_b32_e32 v32, v33
	s_nop 0
	s_and_saveexec_b64 s[72:73], s[6:7]
	s_cbranch_execz .LBB0_725
	v_lshlrev_b64 v[34:35], 6, v[48:49]
	v_lshl_add_u64 v[34:35], s[94:95], 0, v[34:35]
	v_lshl_add_u64 v[34:35], s[66:67], 2, v[34:35]
	s_lshl_b32 s48, s87, 2
	v_lshl_add_u64 v[34:35], v[34:35], 0, s[48:49]
	s_waitcnt lgkmcnt(0)
	v_add_f32_e32 v32, v32, v33
	global_store_dword v[34:35], v32, off

.LBB0_743:
	v_mul_f32_e32 v28, v28, v28
	v_mul_f32_e32 v24, v24, v24
	v_mul_f32_e32 v16, v16, v16
	v_fmac_f32_e32 v28, v29, v29
	v_fmac_f32_e32 v24, v25, v25
	v_mul_f32_e32 v20, v20, v20
	v_fmac_f32_e32 v16, v17, v17
	v_fmac_f32_e32 v28, v30, v30
	v_fmac_f32_e32 v24, v26, v26
	v_fmac_f32_e32 v20, v21, v21
	v_fmac_f32_e32 v16, v18, v18
	v_and_b32_e32 v18, 64, v197
	v_fmac_f32_e32 v28, v31, v31
	v_fmac_f32_e32 v24, v27, v27
	v_fmac_f32_e32 v20, v22, v22
	v_xor_b32_e32 v17, 16, v197
	v_add_u32_e32 v18, 64, v18
	v_add_f32_e32 v24, v28, v24
	v_fmac_f32_e32 v20, v23, v23
	v_cmp_lt_i32_e32 vcc, v17, v18
	v_add_f32_e32 v20, v24, v20
	v_fmac_f32_e32 v16, v19, v19
	v_cndmask_b32_e32 v17, v197, v17, vcc
	v_add_f32_e32 v16, v20, v16
	v_lshlrev_b32_e32 v17, 2, v17
	v_mov_b32_e32 v17, v16
	s_nop 1
	v_permlane16_swap_b32_e32 v16, v17
	s_nop 0
	s_waitcnt lgkmcnt(0)
	v_add_f32_e32 v16, v16, v17
	v_xor_b32_e32 v17, 32, v197
	v_cmp_lt_i32_e32 vcc, v17, v18
	s_nop 1
	v_cndmask_b32_e32 v17, v197, v17, vcc
	v_lshlrev_b32_e32 v17, 2, v17
	v_mov_b32_e32 v17, v16
	s_nop 1
	v_permlane32_swap_b32_e32 v16, v17
	s_nop 0
	s_and_saveexec_b64 s[72:73], s[6:7]
	s_cbranch_execz .LBB0_745
	v_lshlrev_b64 v[18:19], 6, v[32:33]
	v_lshl_add_u64 v[18:19], s[94:95], 0, v[18:19]
	v_lshl_add_u64 v[18:19], s[66:67], 2, v[18:19]
	s_lshl_b32 s48, s87, 2
	v_lshl_add_u64 v[18:19], v[18:19], 0, s[48:49]
	s_waitcnt lgkmcnt(0)
	v_add_f32_e32 v16, v16, v17
	global_store_dword v[18:19], v16, off

.LBB0_764:
	v_mul_f32_e32 v12, v12, v12
	v_mul_f32_e32 v8, v8, v8
	v_mul_f32_e32 v0, v0, v0
	v_fmac_f32_e32 v12, v13, v13
	v_fmac_f32_e32 v8, v9, v9
	v_mul_f32_e32 v4, v4, v4
	v_fmac_f32_e32 v0, v1, v1
	v_fmac_f32_e32 v12, v14, v14
	v_fmac_f32_e32 v8, v10, v10
	v_fmac_f32_e32 v4, v5, v5
	v_fmac_f32_e32 v0, v2, v2
	v_and_b32_e32 v2, 64, v197
	v_fmac_f32_e32 v12, v15, v15
	v_fmac_f32_e32 v8, v11, v11
	v_fmac_f32_e32 v4, v6, v6
	v_xor_b32_e32 v1, 16, v197
	v_add_u32_e32 v2, 64, v2
	v_add_f32_e32 v8, v12, v8
	v_fmac_f32_e32 v4, v7, v7
	v_cmp_lt_i32_e32 vcc, v1, v2
	v_add_f32_e32 v4, v8, v4
	v_fmac_f32_e32 v0, v3, v3
	v_cndmask_b32_e32 v1, v197, v1, vcc
	v_add_f32_e32 v0, v4, v0
	v_lshlrev_b32_e32 v1, 2, v1
	v_mov_b32_e32 v1, v0
	s_nop 1
	v_permlane16_swap_b32_e32 v0, v1
	s_nop 0
	s_waitcnt lgkmcnt(0)
	v_add_f32_e32 v0, v0, v1
	v_xor_b32_e32 v1, 32, v197
	v_cmp_lt_i32_e32 vcc, v1, v2
	s_nop 1
	v_cndmask_b32_e32 v1, v197, v1, vcc
	v_lshlrev_b32_e32 v1, 2, v1
	v_mov_b32_e32 v1, v0
	s_nop 1
	v_permlane32_swap_b32_e32 v0, v1
	s_nop 0
	s_and_saveexec_b64 s[10:11], s[6:7]
	s_cbranch_execz .LBB0_766
	v_lshlrev_b64 v[2:3], 6, v[16:17]
	v_lshl_add_u64 v[2:3], s[94:95], 0, v[2:3]
	v_lshl_add_u64 v[2:3], s[66:67], 2, v[2:3]
	s_lshl_b32 s48, s87, 2
	v_lshl_add_u64 v[2:3], v[2:3], 0, s[48:49]
	s_waitcnt lgkmcnt(0)
	v_add_f32_e32 v0, v0, v1
	global_store_dword v[2:3], v0, off
